# PEER step-B (product-key top-16 merge) rewritten as a compact loop with v_med3_u32 network; 8KB less straight-line code
# speedup vs baseline: 1.2049x; 1.0045x over previous
; #define MONO_KEY(v_, m_, t_) mono_key((v_), (m_), (t_))
; __device__ __forceinline__ void ph_peer(const P& p, int l, int nrows, char* smem, int dryc) {
;     ...
;     if (tid < ntok * 8) {
;       int tok = tid >> 3, h = tid & 7;
;       const float* v1 = sLV + (tok * 16 + h * 2) * 16; const float* v2 = v1 + 16;
;       const int* i1 = sLI + (tok * 16 + h * 2) * 16; const int* i2 = i1 + 16;
;       float a1[16], a2[16];
; #pragma unroll
;       for (int q = 0; q < 16; q++) { a1[q] = v1[q]; a2[q] = v2[q]; }
;       u32 tk[16];
; #pragma unroll
;       for (int q = 0; q < 16; q++) tk[q] = 0u;
; #pragma unroll
;       for (int a = 0; a < 16; a++) {
; #pragma unroll
;         for (int bq = 0; bq < 16; bq++) {
;           if ((a + 1) * (bq + 1) <= 16) { KEY_INSERT(MONO_KEY(a1[a] + a2[bq], 255u, 255 - (a * 16 + bq))); }
;         }
;       }
.LBB0_655:
	s_or_b64 exec, exec, s[12:13]
	s_waitcnt lgkmcnt(0)
	s_barrier
	s_and_saveexec_b64 s[12:13], s[6:7]
	s_cbranch_execz .LBB0_657
	s_waitcnt vmcnt(0) lgkmcnt(0)
	ds_read_b128 v[16:19], v230 offset:64
	ds_read_b128 v[20:23], v230 offset:80
	ds_read_b128 v[24:27], v230 offset:96
	ds_read_b128 v[28:31], v230 offset:112
	ds_read_b32 v48, v230
	v_mov_b32_e32 v52, v230
	v_mov_b32_e32 v32, 0
	v_mov_b32_e32 v33, 0
	v_mov_b32_e32 v34, 0
	v_mov_b32_e32 v35, 0
	v_mov_b32_e32 v36, 0
	v_mov_b32_e32 v37, 0
	v_mov_b32_e32 v38, 0
	v_mov_b32_e32 v39, 0
	v_mov_b32_e32 v40, 0
	v_mov_b32_e32 v41, 0
	v_mov_b32_e32 v42, 0
	v_mov_b32_e32 v43, 0
	v_mov_b32_e32 v44, 0
	v_mov_b32_e32 v45, 0
	v_mov_b32_e32 v46, 0
	v_mov_b32_e32 v47, 0
	s_mov_b32 s14, 0x1112347f
	s_movk_i32 s15, 0xff
	s_mov_b32 s16, 0
	s_waitcnt lgkmcnt(0)
.Lsb_outer:
	s_and_b32 s17, s14, 15
	s_lshr_b32 s14, s14, 4
	v_add_u32_e32 v52, 4, v52
	ds_read_b32 v49, v52
	v_add_f32_e32 v50, v48, v16
	v_ashrrev_i32_e32 v51, 31, v50
	v_or_b32_e32 v51, 0x80000000, v51
	v_xor_b32_e32 v50, v50, v51
	v_and_b32_e32 v50, 0xffffff00, v50
	v_add3_u32 v50, s15, v50, 0
	v_med3_u32 v47, v46, v47, v50
	v_med3_u32 v46, v45, v46, v50
	v_med3_u32 v45, v44, v45, v50
	v_med3_u32 v44, v43, v44, v50
	v_med3_u32 v43, v42, v43, v50
	v_med3_u32 v42, v41, v42, v50
	v_med3_u32 v41, v40, v41, v50
	v_med3_u32 v40, v39, v40, v50
	v_med3_u32 v39, v38, v39, v50
	v_med3_u32 v38, v37, v38, v50
	v_med3_u32 v37, v36, v37, v50
	v_med3_u32 v36, v35, v36, v50
	v_med3_u32 v35, v34, v35, v50
	v_med3_u32 v34, v33, v34, v50
	v_med3_u32 v33, v32, v33, v50
	v_max_u32_e32 v32, v32, v50
	s_cmp_lt_u32 s17, 1
	s_cbranch_scc1 .Lsb_next
	v_add_f32_e32 v50, v48, v17
	v_ashrrev_i32_e32 v51, 31, v50
	v_or_b32_e32 v51, 0x80000000, v51
	v_xor_b32_e32 v50, v50, v51
	v_and_b32_e32 v50, 0xffffff00, v50
	v_add3_u32 v50, s15, v50, -1
	v_med3_u32 v47, v46, v47, v50
	v_med3_u32 v46, v45, v46, v50
	v_med3_u32 v45, v44, v45, v50
	v_med3_u32 v44, v43, v44, v50
	v_med3_u32 v43, v42, v43, v50
	v_med3_u32 v42, v41, v42, v50
	v_med3_u32 v41, v40, v41, v50
	v_med3_u32 v40, v39, v40, v50
	v_med3_u32 v39, v38, v39, v50
	v_med3_u32 v38, v37, v38, v50
	v_med3_u32 v37, v36, v37, v50
	v_med3_u32 v36, v35, v36, v50
	v_med3_u32 v35, v34, v35, v50
	v_med3_u32 v34, v33, v34, v50
	v_med3_u32 v33, v32, v33, v50
	v_max_u32_e32 v32, v32, v50
	s_cmp_lt_u32 s17, 2
	s_cbranch_scc1 .Lsb_next
	v_add_f32_e32 v50, v48, v18
	v_ashrrev_i32_e32 v51, 31, v50
	v_or_b32_e32 v51, 0x80000000, v51
	v_xor_b32_e32 v50, v50, v51
	v_and_b32_e32 v50, 0xffffff00, v50
	v_add3_u32 v50, s15, v50, -2
	v_med3_u32 v47, v46, v47, v50
	v_med3_u32 v46, v45, v46, v50
	v_med3_u32 v45, v44, v45, v50
	v_med3_u32 v44, v43, v44, v50
	v_med3_u32 v43, v42, v43, v50
	v_med3_u32 v42, v41, v42, v50
	v_med3_u32 v41, v40, v41, v50
	v_med3_u32 v40, v39, v40, v50
	v_med3_u32 v39, v38, v39, v50
	v_med3_u32 v38, v37, v38, v50
	v_med3_u32 v37, v36, v37, v50
	v_med3_u32 v36, v35, v36, v50
	v_med3_u32 v35, v34, v35, v50
	v_med3_u32 v34, v33, v34, v50
	v_med3_u32 v33, v32, v33, v50
	v_max_u32_e32 v32, v32, v50
	s_cmp_lt_u32 s17, 3
	s_cbranch_scc1 .Lsb_next
	v_add_f32_e32 v50, v48, v19
	v_ashrrev_i32_e32 v51, 31, v50
	v_or_b32_e32 v51, 0x80000000, v51
	v_xor_b32_e32 v50, v50, v51
	v_and_b32_e32 v50, 0xffffff00, v50
	v_add3_u32 v50, s15, v50, -3
	v_med3_u32 v47, v46, v47, v50
	v_med3_u32 v46, v45, v46, v50
	v_med3_u32 v45, v44, v45, v50
	v_med3_u32 v44, v43, v44, v50
	v_med3_u32 v43, v42, v43, v50
	v_med3_u32 v42, v41, v42, v50
	v_med3_u32 v41, v40, v41, v50
	v_med3_u32 v40, v39, v40, v50
	v_med3_u32 v39, v38, v39, v50
	v_med3_u32 v38, v37, v38, v50
	v_med3_u32 v37, v36, v37, v50
	v_med3_u32 v36, v35, v36, v50
	v_med3_u32 v35, v34, v35, v50
	v_med3_u32 v34, v33, v34, v50
	v_med3_u32 v33, v32, v33, v50
	v_max_u32_e32 v32, v32, v50
	s_cmp_lt_u32 s17, 4
	s_cbranch_scc1 .Lsb_next
	v_add_f32_e32 v50, v48, v20
	v_ashrrev_i32_e32 v51, 31, v50
	v_or_b32_e32 v51, 0x80000000, v51
	v_xor_b32_e32 v50, v50, v51
	v_and_b32_e32 v50, 0xffffff00, v50
	v_add3_u32 v50, s15, v50, -4
	v_med3_u32 v47, v46, v47, v50
	v_med3_u32 v46, v45, v46, v50
	v_med3_u32 v45, v44, v45, v50
	v_med3_u32 v44, v43, v44, v50
	v_med3_u32 v43, v42, v43, v50
	v_med3_u32 v42, v41, v42, v50
	v_med3_u32 v41, v40, v41, v50
	v_med3_u32 v40, v39, v40, v50
	v_med3_u32 v39, v38, v39, v50
	v_med3_u32 v38, v37, v38, v50
	v_med3_u32 v37, v36, v37, v50
	v_med3_u32 v36, v35, v36, v50
	v_med3_u32 v35, v34, v35, v50
	v_med3_u32 v34, v33, v34, v50
	v_med3_u32 v33, v32, v33, v50
	v_max_u32_e32 v32, v32, v50
	s_cmp_lt_u32 s17, 5
	s_cbranch_scc1 .Lsb_next
	v_add_f32_e32 v50, v48, v21
	v_ashrrev_i32_e32 v51, 31, v50
	v_or_b32_e32 v51, 0x80000000, v51
	v_xor_b32_e32 v50, v50, v51
	v_and_b32_e32 v50, 0xffffff00, v50
	v_add3_u32 v50, s15, v50, -5
	v_med3_u32 v47, v46, v47, v50
	v_med3_u32 v46, v45, v46, v50
	v_med3_u32 v45, v44, v45, v50
	v_med3_u32 v44, v43, v44, v50
	v_med3_u32 v43, v42, v43, v50
	v_med3_u32 v42, v41, v42, v50
	v_med3_u32 v41, v40, v41, v50
	v_med3_u32 v40, v39, v40, v50
	v_med3_u32 v39, v38, v39, v50
	v_med3_u32 v38, v37, v38, v50
	v_med3_u32 v37, v36, v37, v50
	v_med3_u32 v36, v35, v36, v50
	v_med3_u32 v35, v34, v35, v50
	v_med3_u32 v34, v33, v34, v50
	v_med3_u32 v33, v32, v33, v50
	v_max_u32_e32 v32, v32, v50
	s_cmp_lt_u32 s17, 6
	s_cbranch_scc1 .Lsb_next
; #define MONO_KEY(v_, m_, t_) mono_key((v_), (m_), (t_))
; __device__ __forceinline__ void ph_peer(const P& p, int l, int nrows, char* smem, int dryc) {
;     ...
;       for (int a = 0; a < 16; a++) {
; #pragma unroll
;         for (int bq = 0; bq < 16; bq++) {
;           if ((a + 1) * (bq + 1) <= 16) { KEY_INSERT(MONO_KEY(a1[a] + a2[bq], 255u, 255 - (a * 16 + bq))); }
;         }
;       }
	v_add_f32_e32 v50, v48, v22
	v_ashrrev_i32_e32 v51, 31, v50
	v_or_b32_e32 v51, 0x80000000, v51
	v_xor_b32_e32 v50, v50, v51
	v_and_b32_e32 v50, 0xffffff00, v50
	v_add3_u32 v50, s15, v50, -6
	v_med3_u32 v47, v46, v47, v50
	v_med3_u32 v46, v45, v46, v50
	v_med3_u32 v45, v44, v45, v50
	v_med3_u32 v44, v43, v44, v50
	v_med3_u32 v43, v42, v43, v50
	v_med3_u32 v42, v41, v42, v50
	v_med3_u32 v41, v40, v41, v50
	v_med3_u32 v40, v39, v40, v50
	v_med3_u32 v39, v38, v39, v50
	v_med3_u32 v38, v37, v38, v50
	v_med3_u32 v37, v36, v37, v50
	v_med3_u32 v36, v35, v36, v50
	v_med3_u32 v35, v34, v35, v50
	v_med3_u32 v34, v33, v34, v50
	v_med3_u32 v33, v32, v33, v50
	v_max_u32_e32 v32, v32, v50
	s_cmp_lt_u32 s17, 7
	s_cbranch_scc1 .Lsb_next
	v_add_f32_e32 v50, v48, v23
	v_ashrrev_i32_e32 v51, 31, v50
	v_or_b32_e32 v51, 0x80000000, v51
	v_xor_b32_e32 v50, v50, v51
	v_and_b32_e32 v50, 0xffffff00, v50
	v_add3_u32 v50, s15, v50, -7
	v_med3_u32 v47, v46, v47, v50
	v_med3_u32 v46, v45, v46, v50
	v_med3_u32 v45, v44, v45, v50
	v_med3_u32 v44, v43, v44, v50
	v_med3_u32 v43, v42, v43, v50
	v_med3_u32 v42, v41, v42, v50
	v_med3_u32 v41, v40, v41, v50
	v_med3_u32 v40, v39, v40, v50
	v_med3_u32 v39, v38, v39, v50
	v_med3_u32 v38, v37, v38, v50
	v_med3_u32 v37, v36, v37, v50
	v_med3_u32 v36, v35, v36, v50
	v_med3_u32 v35, v34, v35, v50
	v_med3_u32 v34, v33, v34, v50
	v_med3_u32 v33, v32, v33, v50
	v_max_u32_e32 v32, v32, v50
	s_cmp_lt_u32 s17, 8
	s_cbranch_scc1 .Lsb_next
	v_add_f32_e32 v50, v48, v24
	v_ashrrev_i32_e32 v51, 31, v50
	v_or_b32_e32 v51, 0x80000000, v51
	v_xor_b32_e32 v50, v50, v51
	v_and_b32_e32 v50, 0xffffff00, v50
	v_add3_u32 v50, s15, v50, -8
	v_med3_u32 v47, v46, v47, v50
	v_med3_u32 v46, v45, v46, v50
	v_med3_u32 v45, v44, v45, v50
	v_med3_u32 v44, v43, v44, v50
	v_med3_u32 v43, v42, v43, v50
	v_med3_u32 v42, v41, v42, v50
	v_med3_u32 v41, v40, v41, v50
	v_med3_u32 v40, v39, v40, v50
	v_med3_u32 v39, v38, v39, v50
	v_med3_u32 v38, v37, v38, v50
	v_med3_u32 v37, v36, v37, v50
	v_med3_u32 v36, v35, v36, v50
	v_med3_u32 v35, v34, v35, v50
	v_med3_u32 v34, v33, v34, v50
	v_med3_u32 v33, v32, v33, v50
	v_max_u32_e32 v32, v32, v50
	s_cmp_lt_u32 s17, 9
	s_cbranch_scc1 .Lsb_next
	v_add_f32_e32 v50, v48, v25
	v_ashrrev_i32_e32 v51, 31, v50
	v_or_b32_e32 v51, 0x80000000, v51
	v_xor_b32_e32 v50, v50, v51
	v_and_b32_e32 v50, 0xffffff00, v50
	v_add3_u32 v50, s15, v50, -9
	v_med3_u32 v47, v46, v47, v50
	v_med3_u32 v46, v45, v46, v50
	v_med3_u32 v45, v44, v45, v50
	v_med3_u32 v44, v43, v44, v50
	v_med3_u32 v43, v42, v43, v50
	v_med3_u32 v42, v41, v42, v50
	v_med3_u32 v41, v40, v41, v50
	v_med3_u32 v40, v39, v40, v50
	v_med3_u32 v39, v38, v39, v50
	v_med3_u32 v38, v37, v38, v50
	v_med3_u32 v37, v36, v37, v50
	v_med3_u32 v36, v35, v36, v50
	v_med3_u32 v35, v34, v35, v50
	v_med3_u32 v34, v33, v34, v50
	v_med3_u32 v33, v32, v33, v50
	v_max_u32_e32 v32, v32, v50
	s_cmp_lt_u32 s17, 10
	s_cbranch_scc1 .Lsb_next
	v_add_f32_e32 v50, v48, v26
	v_ashrrev_i32_e32 v51, 31, v50
	v_or_b32_e32 v51, 0x80000000, v51
	v_xor_b32_e32 v50, v50, v51
	v_and_b32_e32 v50, 0xffffff00, v50
	v_add3_u32 v50, s15, v50, -10
	v_med3_u32 v47, v46, v47, v50
	v_med3_u32 v46, v45, v46, v50
	v_med3_u32 v45, v44, v45, v50
	v_med3_u32 v44, v43, v44, v50
	v_med3_u32 v43, v42, v43, v50
	v_med3_u32 v42, v41, v42, v50
	v_med3_u32 v41, v40, v41, v50
	v_med3_u32 v40, v39, v40, v50
	v_med3_u32 v39, v38, v39, v50
	v_med3_u32 v38, v37, v38, v50
	v_med3_u32 v37, v36, v37, v50
	v_med3_u32 v36, v35, v36, v50
	v_med3_u32 v35, v34, v35, v50
	v_med3_u32 v34, v33, v34, v50
	v_med3_u32 v33, v32, v33, v50
	v_max_u32_e32 v32, v32, v50
	s_cmp_lt_u32 s17, 11
	s_cbranch_scc1 .Lsb_next
	v_add_f32_e32 v50, v48, v27
	v_ashrrev_i32_e32 v51, 31, v50
	v_or_b32_e32 v51, 0x80000000, v51
	v_xor_b32_e32 v50, v50, v51
	v_and_b32_e32 v50, 0xffffff00, v50
	v_add3_u32 v50, s15, v50, -11
	v_med3_u32 v47, v46, v47, v50
	v_med3_u32 v46, v45, v46, v50
	v_med3_u32 v45, v44, v45, v50
	v_med3_u32 v44, v43, v44, v50
	v_med3_u32 v43, v42, v43, v50
	v_med3_u32 v42, v41, v42, v50
	v_med3_u32 v41, v40, v41, v50
	v_med3_u32 v40, v39, v40, v50
	v_med3_u32 v39, v38, v39, v50
	v_med3_u32 v38, v37, v38, v50
	v_med3_u32 v37, v36, v37, v50
	v_med3_u32 v36, v35, v36, v50
	v_med3_u32 v35, v34, v35, v50
	v_med3_u32 v34, v33, v34, v50
	v_med3_u32 v33, v32, v33, v50
	v_max_u32_e32 v32, v32, v50
	s_cmp_lt_u32 s17, 12
	s_cbranch_scc1 .Lsb_next
	v_add_f32_e32 v50, v48, v28
	v_ashrrev_i32_e32 v51, 31, v50
	v_or_b32_e32 v51, 0x80000000, v51
	v_xor_b32_e32 v50, v50, v51
	v_and_b32_e32 v50, 0xffffff00, v50
	v_add3_u32 v50, s15, v50, -12
	v_med3_u32 v47, v46, v47, v50
	v_med3_u32 v46, v45, v46, v50
	v_med3_u32 v45, v44, v45, v50
	v_med3_u32 v44, v43, v44, v50
	v_med3_u32 v43, v42, v43, v50
	v_med3_u32 v42, v41, v42, v50
	v_med3_u32 v41, v40, v41, v50
	v_med3_u32 v40, v39, v40, v50
	v_med3_u32 v39, v38, v39, v50
	v_med3_u32 v38, v37, v38, v50
	v_med3_u32 v37, v36, v37, v50
	v_med3_u32 v36, v35, v36, v50
	v_med3_u32 v35, v34, v35, v50
	v_med3_u32 v34, v33, v34, v50
	v_med3_u32 v33, v32, v33, v50
	v_max_u32_e32 v32, v32, v50
	s_cmp_lt_u32 s17, 13
	s_cbranch_scc1 .Lsb_next
	v_add_f32_e32 v50, v48, v29
	v_ashrrev_i32_e32 v51, 31, v50
	v_or_b32_e32 v51, 0x80000000, v51
	v_xor_b32_e32 v50, v50, v51
	v_and_b32_e32 v50, 0xffffff00, v50
	v_add3_u32 v50, s15, v50, -13
	v_med3_u32 v47, v46, v47, v50
	v_med3_u32 v46, v45, v46, v50
	v_med3_u32 v45, v44, v45, v50
	v_med3_u32 v44, v43, v44, v50
	v_med3_u32 v43, v42, v43, v50
	v_med3_u32 v42, v41, v42, v50
	v_med3_u32 v41, v40, v41, v50
	v_med3_u32 v40, v39, v40, v50
	v_med3_u32 v39, v38, v39, v50
	v_med3_u32 v38, v37, v38, v50
	v_med3_u32 v37, v36, v37, v50
	v_med3_u32 v36, v35, v36, v50
	v_med3_u32 v35, v34, v35, v50
	v_med3_u32 v34, v33, v34, v50
	v_med3_u32 v33, v32, v33, v50
	v_max_u32_e32 v32, v32, v50
	s_cmp_lt_u32 s17, 14
	s_cbranch_scc1 .Lsb_next
; #define MONO_KEY(v_, m_, t_) mono_key((v_), (m_), (t_))
; #define KEY_VALUE(k_, m_) key_value((k_), (m_))
; __device__ __forceinline__ void ph_peer(const P& p, int l, int nrows, char* smem, int dryc) {
;     ...
;       for (int a = 0; a < 16; a++) {
; #pragma unroll
;         for (int bq = 0; bq < 16; bq++) {
;           if ((a + 1) * (bq + 1) <= 16) { KEY_INSERT(MONO_KEY(a1[a] + a2[bq], 255u, 255 - (a * 16 + bq))); }
;         }
;       }
;       float mx = KEY_VALUE(tk[0], 255u); float sum = 0.f; float ex[16];
; #pragma unroll
;       for (int q = 0; q < 16; q++) { ex[q] = __expf(KEY_VALUE(tk[q], 255u) - mx); sum += ex[q]; }
	v_add_f32_e32 v50, v48, v30
	v_ashrrev_i32_e32 v51, 31, v50
	v_or_b32_e32 v51, 0x80000000, v51
	v_xor_b32_e32 v50, v50, v51
	v_and_b32_e32 v50, 0xffffff00, v50
	v_add3_u32 v50, s15, v50, -14
	v_med3_u32 v47, v46, v47, v50
	v_med3_u32 v46, v45, v46, v50
	v_med3_u32 v45, v44, v45, v50
	v_med3_u32 v44, v43, v44, v50
	v_med3_u32 v43, v42, v43, v50
	v_med3_u32 v42, v41, v42, v50
	v_med3_u32 v41, v40, v41, v50
	v_med3_u32 v40, v39, v40, v50
	v_med3_u32 v39, v38, v39, v50
	v_med3_u32 v38, v37, v38, v50
	v_med3_u32 v37, v36, v37, v50
	v_med3_u32 v36, v35, v36, v50
	v_med3_u32 v35, v34, v35, v50
	v_med3_u32 v34, v33, v34, v50
	v_med3_u32 v33, v32, v33, v50
	v_max_u32_e32 v32, v32, v50
	s_cmp_lt_u32 s17, 15
	s_cbranch_scc1 .Lsb_next
	v_add_f32_e32 v50, v48, v31
	v_ashrrev_i32_e32 v51, 31, v50
	v_or_b32_e32 v51, 0x80000000, v51
	v_xor_b32_e32 v50, v50, v51
	v_and_b32_e32 v50, 0xffffff00, v50
	v_add3_u32 v50, s15, v50, -15
	v_med3_u32 v47, v46, v47, v50
	v_med3_u32 v46, v45, v46, v50
	v_med3_u32 v45, v44, v45, v50
	v_med3_u32 v44, v43, v44, v50
	v_med3_u32 v43, v42, v43, v50
	v_med3_u32 v42, v41, v42, v50
	v_med3_u32 v41, v40, v41, v50
	v_med3_u32 v40, v39, v40, v50
	v_med3_u32 v39, v38, v39, v50
	v_med3_u32 v38, v37, v38, v50
	v_med3_u32 v37, v36, v37, v50
	v_med3_u32 v36, v35, v36, v50
	v_med3_u32 v35, v34, v35, v50
	v_med3_u32 v34, v33, v34, v50
	v_med3_u32 v33, v32, v33, v50
	v_max_u32_e32 v32, v32, v50
.Lsb_next:
	s_add_i32 s16, s16, 1
	s_sub_i32 s15, s15, 16
	s_waitcnt lgkmcnt(0)
	v_mov_b32_e32 v48, v49
	s_cmp_lt_u32 s16, 16
	s_cbranch_scc1 .Lsb_outer
	v_and_b32_e32 v60, 0x7fffff00, v32
	v_not_b32_e32 v61, v32
	v_or_b32_e32 v61, 0xff, v61
	v_cmp_gt_i32_e32 vcc, 0, v32
	s_nop 1
	v_cndmask_b32_e32 v64, v61, v60, vcc
	v_and_b32_e32 v60, 0x7fffff00, v33
	v_not_b32_e32 v61, v33
	v_or_b32_e32 v61, 0xff, v61
	v_cmp_gt_i32_e32 vcc, 0, v33
	s_nop 1
	v_cndmask_b32_e32 v65, v61, v60, vcc
	v_and_b32_e32 v60, 0x7fffff00, v34
	v_not_b32_e32 v61, v34
	v_or_b32_e32 v61, 0xff, v61
	v_cmp_gt_i32_e32 vcc, 0, v34
	s_nop 1
	v_cndmask_b32_e32 v66, v61, v60, vcc
	v_and_b32_e32 v60, 0x7fffff00, v35
	v_not_b32_e32 v61, v35
	v_or_b32_e32 v61, 0xff, v61
	v_cmp_gt_i32_e32 vcc, 0, v35
	s_nop 1
	v_cndmask_b32_e32 v67, v61, v60, vcc
	v_and_b32_e32 v60, 0x7fffff00, v36
	v_not_b32_e32 v61, v36
	v_or_b32_e32 v61, 0xff, v61
	v_cmp_gt_i32_e32 vcc, 0, v36
	s_nop 1
	v_cndmask_b32_e32 v68, v61, v60, vcc
	v_and_b32_e32 v60, 0x7fffff00, v37
	v_not_b32_e32 v61, v37
	v_or_b32_e32 v61, 0xff, v61
	v_cmp_gt_i32_e32 vcc, 0, v37
	s_nop 1
	v_cndmask_b32_e32 v69, v61, v60, vcc
	v_and_b32_e32 v60, 0x7fffff00, v38
	v_not_b32_e32 v61, v38
	v_or_b32_e32 v61, 0xff, v61
	v_cmp_gt_i32_e32 vcc, 0, v38
	s_nop 1
	v_cndmask_b32_e32 v70, v61, v60, vcc
	v_and_b32_e32 v60, 0x7fffff00, v39
	v_not_b32_e32 v61, v39
	v_or_b32_e32 v61, 0xff, v61
	v_cmp_gt_i32_e32 vcc, 0, v39
	s_nop 1
	v_cndmask_b32_e32 v71, v61, v60, vcc
	v_and_b32_e32 v60, 0x7fffff00, v40
	v_not_b32_e32 v61, v40
	v_or_b32_e32 v61, 0xff, v61
	v_cmp_gt_i32_e32 vcc, 0, v40
	s_nop 1
	v_cndmask_b32_e32 v72, v61, v60, vcc
	v_and_b32_e32 v60, 0x7fffff00, v41
	v_not_b32_e32 v61, v41
	v_or_b32_e32 v61, 0xff, v61
	v_cmp_gt_i32_e32 vcc, 0, v41
	s_nop 1
	v_cndmask_b32_e32 v73, v61, v60, vcc
	v_and_b32_e32 v60, 0x7fffff00, v42
	v_not_b32_e32 v61, v42
	v_or_b32_e32 v61, 0xff, v61
	v_cmp_gt_i32_e32 vcc, 0, v42
	s_nop 1
	v_cndmask_b32_e32 v74, v61, v60, vcc
	v_and_b32_e32 v60, 0x7fffff00, v43
	v_not_b32_e32 v61, v43
	v_or_b32_e32 v61, 0xff, v61
	v_cmp_gt_i32_e32 vcc, 0, v43
	s_nop 1
	v_cndmask_b32_e32 v75, v61, v60, vcc
	v_and_b32_e32 v60, 0x7fffff00, v44
	v_not_b32_e32 v61, v44
	v_or_b32_e32 v61, 0xff, v61
	v_cmp_gt_i32_e32 vcc, 0, v44
	s_nop 1
	v_cndmask_b32_e32 v76, v61, v60, vcc
	v_and_b32_e32 v60, 0x7fffff00, v45
	v_not_b32_e32 v61, v45
	v_or_b32_e32 v61, 0xff, v61
	v_cmp_gt_i32_e32 vcc, 0, v45
	s_nop 1
	v_cndmask_b32_e32 v77, v61, v60, vcc
	v_and_b32_e32 v60, 0x7fffff00, v46
	v_not_b32_e32 v61, v46
	v_or_b32_e32 v61, 0xff, v61
	v_cmp_gt_i32_e32 vcc, 0, v46
	s_nop 1
	v_cndmask_b32_e32 v78, v61, v60, vcc
	v_and_b32_e32 v60, 0x7fffff00, v47
	v_not_b32_e32 v61, v47
	v_or_b32_e32 v61, 0xff, v61
	v_cmp_gt_i32_e32 vcc, 0, v47
	s_nop 1
	v_cndmask_b32_e32 v79, v61, v60, vcc
	v_sub_f32_e32 v60, v64, v64
	v_mul_f32_e32 v60, 0x3fb8aa3b, v60
	v_exp_f32_e32 v80, v60
	v_sub_f32_e32 v60, v65, v64
	v_mul_f32_e32 v60, 0x3fb8aa3b, v60
	v_exp_f32_e32 v81, v60
	v_sub_f32_e32 v60, v66, v64
	v_mul_f32_e32 v60, 0x3fb8aa3b, v60
	v_exp_f32_e32 v82, v60
	v_sub_f32_e32 v60, v67, v64
	v_mul_f32_e32 v60, 0x3fb8aa3b, v60
	v_exp_f32_e32 v83, v60
	v_sub_f32_e32 v60, v68, v64
	v_mul_f32_e32 v60, 0x3fb8aa3b, v60
	v_exp_f32_e32 v84, v60
	v_sub_f32_e32 v60, v69, v64
	v_mul_f32_e32 v60, 0x3fb8aa3b, v60
	v_exp_f32_e32 v85, v60
	v_sub_f32_e32 v60, v70, v64
	v_mul_f32_e32 v60, 0x3fb8aa3b, v60
	v_exp_f32_e32 v86, v60
	v_sub_f32_e32 v60, v71, v64
	v_mul_f32_e32 v60, 0x3fb8aa3b, v60
	v_exp_f32_e32 v87, v60
	v_sub_f32_e32 v60, v72, v64
	v_mul_f32_e32 v60, 0x3fb8aa3b, v60
	v_exp_f32_e32 v88, v60
	v_sub_f32_e32 v60, v73, v64
	v_mul_f32_e32 v60, 0x3fb8aa3b, v60
	v_exp_f32_e32 v89, v60
	v_sub_f32_e32 v60, v74, v64
	v_mul_f32_e32 v60, 0x3fb8aa3b, v60
	v_exp_f32_e32 v90, v60
	v_sub_f32_e32 v60, v75, v64
	v_mul_f32_e32 v60, 0x3fb8aa3b, v60
	v_exp_f32_e32 v91, v60
	v_sub_f32_e32 v60, v76, v64
	v_mul_f32_e32 v60, 0x3fb8aa3b, v60
	v_exp_f32_e32 v92, v60
	v_sub_f32_e32 v60, v77, v64
	v_mul_f32_e32 v60, 0x3fb8aa3b, v60
	v_exp_f32_e32 v93, v60
	v_sub_f32_e32 v60, v78, v64
	v_mul_f32_e32 v60, 0x3fb8aa3b, v60
	v_exp_f32_e32 v94, v60
	v_sub_f32_e32 v60, v79, v64
	v_mul_f32_e32 v60, 0x3fb8aa3b, v60
; #define KEY_VALUE(k_, m_) key_value((k_), (m_))
; __device__ __forceinline__ void ph_peer(const P& p, int l, int nrows, char* smem, int dryc) {
;     ...
;       float mx = KEY_VALUE(tk[0], 255u); float sum = 0.f; float ex[16];
; #pragma unroll
;       for (int q = 0; q < 16; q++) { ex[q] = __expf(KEY_VALUE(tk[q], 255u) - mx); sum += ex[q]; }
;       float inv = 1.f / sum;
; #pragma unroll
;       for (int q = 0; q < 16; q++) {
;         int ci = 255 - (int)(tk[q] & 255u);
;         int e = i1[ci >> 4] * 128 + i2[ci & 15];
	v_exp_f32_e32 v95, v60
	s_nop 0
	v_mov_b32_e32 v62, v80
	v_add_f32_e32 v62, v81, v62
	v_add_f32_e32 v62, v82, v62
	v_add_f32_e32 v62, v83, v62
	v_add_f32_e32 v62, v84, v62
	v_add_f32_e32 v62, v85, v62
	v_add_f32_e32 v62, v86, v62
	v_add_f32_e32 v62, v87, v62
	v_add_f32_e32 v62, v88, v62
	v_add_f32_e32 v62, v89, v62
	v_add_f32_e32 v62, v90, v62
	v_add_f32_e32 v62, v91, v62
	v_add_f32_e32 v62, v92, v62
	v_add_f32_e32 v62, v93, v62
	v_add_f32_e32 v62, v94, v62
	v_add_f32_e32 v62, v95, v62
	v_div_scale_f32 v57, s[0:1], v62, v62, 1.0
	v_rcp_f32_e32 v58, v57
	s_nop 0
	v_fma_f32 v59, -v57, v58, 1.0
	v_fmac_f32_e32 v58, v59, v58
	v_div_scale_f32 v59, vcc, 1.0, v62, 1.0
	v_mul_f32_e32 v63, v59, v58
	v_fma_f32 v56, -v57, v63, v59
	v_fmac_f32_e32 v63, v56, v58
	v_fma_f32 v57, -v57, v63, v59
	v_div_fmas_f32 v57, v57, v58, v63
	v_div_fixup_f32 v62, v57, v62, 1.0
	v_mul_f32_e32 v112, v80, v62
	v_mul_f32_e32 v113, v81, v62
	v_mul_f32_e32 v114, v82, v62
	v_mul_f32_e32 v115, v83, v62
	v_mul_f32_e32 v116, v84, v62
	v_mul_f32_e32 v117, v85, v62
	v_mul_f32_e32 v118, v86, v62
	v_mul_f32_e32 v119, v87, v62
	v_mul_f32_e32 v120, v88, v62
	v_mul_f32_e32 v121, v89, v62
	v_mul_f32_e32 v122, v90, v62
	v_mul_f32_e32 v123, v91, v62
	v_mul_f32_e32 v124, v92, v62
	v_mul_f32_e32 v125, v93, v62
	v_mul_f32_e32 v126, v94, v62
	v_mul_f32_e32 v127, v95, v62
	v_not_b32_e32 v60, v32
	v_lshrrev_b32_e32 v61, 2, v60
	v_and_b32_e32 v61, 60, v61
	v_add_u32_e32 v61, v230, v61
	v_and_b32_e32 v60, 15, v60
	v_lshl_add_u32 v60, v60, 2, v230
	ds_read_b32 v0, v61 offset:16384
	ds_read_b32 v4, v60 offset:16448
	v_not_b32_e32 v60, v33
	v_lshrrev_b32_e32 v61, 2, v60
	v_and_b32_e32 v61, 60, v61
	v_add_u32_e32 v61, v230, v61
	v_and_b32_e32 v60, 15, v60
	v_lshl_add_u32 v60, v60, 2, v230
	ds_read_b32 v1, v61 offset:16384
	ds_read_b32 v5, v60 offset:16448
	v_not_b32_e32 v60, v34
	v_lshrrev_b32_e32 v61, 2, v60
	v_and_b32_e32 v61, 60, v61
	v_add_u32_e32 v61, v230, v61
	v_and_b32_e32 v60, 15, v60
	v_lshl_add_u32 v60, v60, 2, v230
	ds_read_b32 v2, v61 offset:16384
	ds_read_b32 v6, v60 offset:16448
	v_not_b32_e32 v60, v35
	v_lshrrev_b32_e32 v61, 2, v60
	v_and_b32_e32 v61, 60, v61
	v_add_u32_e32 v61, v230, v61
	v_and_b32_e32 v60, 15, v60
	v_lshl_add_u32 v60, v60, 2, v230
	ds_read_b32 v3, v61 offset:16384
	ds_read_b32 v7, v60 offset:16448
	s_waitcnt lgkmcnt(0)
	v_lshl_add_u32 v96, v0, 7, v4
	v_lshl_add_u32 v97, v1, 7, v5
	v_lshl_add_u32 v98, v2, 7, v6
	v_lshl_add_u32 v99, v3, 7, v7
	v_not_b32_e32 v60, v36
	v_lshrrev_b32_e32 v61, 2, v60
	v_and_b32_e32 v61, 60, v61
	v_add_u32_e32 v61, v230, v61
	v_and_b32_e32 v60, 15, v60
	v_lshl_add_u32 v60, v60, 2, v230
	ds_read_b32 v0, v61 offset:16384
	ds_read_b32 v4, v60 offset:16448
	v_not_b32_e32 v60, v37
	v_lshrrev_b32_e32 v61, 2, v60
	v_and_b32_e32 v61, 60, v61
	v_add_u32_e32 v61, v230, v61
	v_and_b32_e32 v60, 15, v60
	v_lshl_add_u32 v60, v60, 2, v230
	ds_read_b32 v1, v61 offset:16384
	ds_read_b32 v5, v60 offset:16448
	v_not_b32_e32 v60, v38
	v_lshrrev_b32_e32 v61, 2, v60
	v_and_b32_e32 v61, 60, v61
	v_add_u32_e32 v61, v230, v61
	v_and_b32_e32 v60, 15, v60
	v_lshl_add_u32 v60, v60, 2, v230
	ds_read_b32 v2, v61 offset:16384
	ds_read_b32 v6, v60 offset:16448
	v_not_b32_e32 v60, v39
	v_lshrrev_b32_e32 v61, 2, v60
	v_and_b32_e32 v61, 60, v61
	v_add_u32_e32 v61, v230, v61
	v_and_b32_e32 v60, 15, v60
	v_lshl_add_u32 v60, v60, 2, v230
	ds_read_b32 v3, v61 offset:16384
	ds_read_b32 v7, v60 offset:16448
	s_waitcnt lgkmcnt(0)
	v_lshl_add_u32 v100, v0, 7, v4
	v_lshl_add_u32 v101, v1, 7, v5
	v_lshl_add_u32 v102, v2, 7, v6
	v_lshl_add_u32 v103, v3, 7, v7
	v_not_b32_e32 v60, v40
	v_lshrrev_b32_e32 v61, 2, v60
	v_and_b32_e32 v61, 60, v61
	v_add_u32_e32 v61, v230, v61
	v_and_b32_e32 v60, 15, v60
	v_lshl_add_u32 v60, v60, 2, v230
	ds_read_b32 v0, v61 offset:16384
	ds_read_b32 v4, v60 offset:16448
	v_not_b32_e32 v60, v41
	v_lshrrev_b32_e32 v61, 2, v60
	v_and_b32_e32 v61, 60, v61
	v_add_u32_e32 v61, v230, v61
	v_and_b32_e32 v60, 15, v60
	v_lshl_add_u32 v60, v60, 2, v230
	ds_read_b32 v1, v61 offset:16384
	ds_read_b32 v5, v60 offset:16448
	v_not_b32_e32 v60, v42
	v_lshrrev_b32_e32 v61, 2, v60
	v_and_b32_e32 v61, 60, v61
	v_add_u32_e32 v61, v230, v61
	v_and_b32_e32 v60, 15, v60
	v_lshl_add_u32 v60, v60, 2, v230
	ds_read_b32 v2, v61 offset:16384
	ds_read_b32 v6, v60 offset:16448
	v_not_b32_e32 v60, v43
	v_lshrrev_b32_e32 v61, 2, v60
	v_and_b32_e32 v61, 60, v61
	v_add_u32_e32 v61, v230, v61
	v_and_b32_e32 v60, 15, v60
	v_lshl_add_u32 v60, v60, 2, v230
	ds_read_b32 v3, v61 offset:16384
	ds_read_b32 v7, v60 offset:16448
	s_waitcnt lgkmcnt(0)
; __device__ __forceinline__ void ph_peer(const P& p, int l, int nrows, char* smem, int dryc) {
;     ...
; #pragma unroll
;       for (int q = 0; q < 16; q++) {
;         int ci = 255 - (int)(tk[q] & 255u);
;         int e = i1[ci >> 4] * 128 + i2[ci & 15];
;         sE[tok * 128 + h * 16 + q] = e;
;         sG[tok * 128 + h * 16 + q] = ex[q] * inv;
;         sSU[tok * 128 + h * 16 + q] = USC[e];
;         sSV[tok * 128 + h * 16 + q] = VSC[e];
;       }
	v_lshl_add_u32 v104, v0, 7, v4
	v_lshl_add_u32 v105, v1, 7, v5
	v_lshl_add_u32 v106, v2, 7, v6
	v_lshl_add_u32 v107, v3, 7, v7
	v_not_b32_e32 v60, v44
	v_lshrrev_b32_e32 v61, 2, v60
	v_and_b32_e32 v61, 60, v61
	v_add_u32_e32 v61, v230, v61
	v_and_b32_e32 v60, 15, v60
	v_lshl_add_u32 v60, v60, 2, v230
	ds_read_b32 v0, v61 offset:16384
	ds_read_b32 v4, v60 offset:16448
	v_not_b32_e32 v60, v45
	v_lshrrev_b32_e32 v61, 2, v60
	v_and_b32_e32 v61, 60, v61
	v_add_u32_e32 v61, v230, v61
	v_and_b32_e32 v60, 15, v60
	v_lshl_add_u32 v60, v60, 2, v230
	ds_read_b32 v1, v61 offset:16384
	ds_read_b32 v5, v60 offset:16448
	v_not_b32_e32 v60, v46
	v_lshrrev_b32_e32 v61, 2, v60
	v_and_b32_e32 v61, 60, v61
	v_add_u32_e32 v61, v230, v61
	v_and_b32_e32 v60, 15, v60
	v_lshl_add_u32 v60, v60, 2, v230
	ds_read_b32 v2, v61 offset:16384
	ds_read_b32 v6, v60 offset:16448
	v_not_b32_e32 v60, v47
	v_lshrrev_b32_e32 v61, 2, v60
	v_and_b32_e32 v61, 60, v61
	v_add_u32_e32 v61, v230, v61
	v_and_b32_e32 v60, 15, v60
	v_lshl_add_u32 v60, v60, 2, v230
	ds_read_b32 v3, v61 offset:16384
	ds_read_b32 v7, v60 offset:16448
	s_waitcnt lgkmcnt(0)
	v_lshl_add_u32 v108, v0, 7, v4
	v_lshl_add_u32 v109, v1, 7, v5
	v_lshl_add_u32 v110, v2, 7, v6
	v_lshl_add_u32 v111, v3, 7, v7
	v_lshlrev_b32_e32 v60, 2, v96
	global_load_dword v0, v60, s[62:63]
	global_load_dword v16, v60, s[64:65]
	v_lshlrev_b32_e32 v60, 2, v97
	global_load_dword v1, v60, s[62:63]
	global_load_dword v17, v60, s[64:65]
	v_lshlrev_b32_e32 v60, 2, v98
	global_load_dword v2, v60, s[62:63]
	global_load_dword v18, v60, s[64:65]
	v_lshlrev_b32_e32 v60, 2, v99
	global_load_dword v3, v60, s[62:63]
	global_load_dword v19, v60, s[64:65]
	v_lshlrev_b32_e32 v60, 2, v100
	global_load_dword v4, v60, s[62:63]
	global_load_dword v20, v60, s[64:65]
	v_lshlrev_b32_e32 v60, 2, v101
	global_load_dword v5, v60, s[62:63]
	global_load_dword v21, v60, s[64:65]
	v_lshlrev_b32_e32 v60, 2, v102
	global_load_dword v6, v60, s[62:63]
	global_load_dword v22, v60, s[64:65]
	v_lshlrev_b32_e32 v60, 2, v103
	global_load_dword v7, v60, s[62:63]
	global_load_dword v23, v60, s[64:65]
	v_lshlrev_b32_e32 v60, 2, v104
	global_load_dword v8, v60, s[62:63]
	global_load_dword v24, v60, s[64:65]
	v_lshlrev_b32_e32 v60, 2, v105
	global_load_dword v9, v60, s[62:63]
	global_load_dword v25, v60, s[64:65]
	v_lshlrev_b32_e32 v60, 2, v106
	global_load_dword v10, v60, s[62:63]
	global_load_dword v26, v60, s[64:65]
	v_lshlrev_b32_e32 v60, 2, v107
	global_load_dword v11, v60, s[62:63]
	global_load_dword v27, v60, s[64:65]
	v_lshlrev_b32_e32 v60, 2, v108
	global_load_dword v12, v60, s[62:63]
	global_load_dword v28, v60, s[64:65]
	v_lshlrev_b32_e32 v60, 2, v109
	global_load_dword v13, v60, s[62:63]
	global_load_dword v29, v60, s[64:65]
	v_lshlrev_b32_e32 v60, 2, v110
	global_load_dword v14, v60, s[62:63]
	global_load_dword v30, v60, s[64:65]
	v_lshlrev_b32_e32 v60, 2, v111
	global_load_dword v15, v60, s[62:63]
	global_load_dword v31, v60, s[64:65]
	ds_write_b128 v237, v[96:99] offset:32768
	ds_write_b128 v237, v[112:115] offset:40960
	ds_write_b128 v237, v[100:103] offset:32784
	ds_write_b128 v237, v[116:119] offset:40976
	ds_write_b128 v237, v[104:107] offset:32800
	ds_write_b128 v237, v[120:123] offset:40992
	ds_write_b128 v237, v[108:111] offset:32816
	ds_write_b128 v237, v[124:127] offset:41008
	s_waitcnt vmcnt(0)
	ds_write_b128 v237, v[0:3] offset:49152
	ds_write_b128 v237, v[16:19] offset:57344
	ds_write_b128 v237, v[4:7] offset:49168
	ds_write_b128 v237, v[20:23] offset:57360
	ds_write_b128 v237, v[8:11] offset:49184
	ds_write_b128 v237, v[24:27] offset:57376
	ds_write_b128 v237, v[12:15] offset:49200
	ds_write_b128 v237, v[28:31] offset:57392
